# v35: v34 + MLA K/V prefetch loads in scalar-base form with SALU-advanced tile pointers (s98-s101)
# speedup vs baseline: 1.0214x; 1.0104x over previous
.LBB0_2709:
	s_or_b64 exec, exec, s[4:5]
	global_load_dwordx4 v[132:135], v[10:11], off offset:256
	s_waitcnt lgkmcnt(0)
	s_barrier
	ds_read_b128 v[0:3], v184
	ds_read_b128 v[4:7], v184 offset:32
	s_waitcnt lgkmcnt(1)
	v_mfma_f32_32x32x16_bf16 v[48:63], v[0:3], v[100:103], 0
	s_mov_b32 s12, 0
	s_mov_b32 s13, s12
	s_mul_hi_i32 s5, s9, 0x108000
	s_mul_i32 s4, s9, 0x108000
	s_mov_b32 s14, s12
	s_mov_b32 s15, s12
	s_mov_b32 s16, s12
	s_waitcnt lgkmcnt(0)
	v_mfma_f32_32x32x16_bf16 v[48:63], v[4:7], v[104:107], v[48:63]
	ds_read_b128 v[0:3], v184 offset:64
	ds_read_b128 v[4:7], v184 offset:96
	s_mov_b32 s17, s12
	s_mov_b32 s18, s12
	s_mov_b32 s19, s12
	s_mov_b32 s20, s12
	s_mov_b32 s21, s12
	s_mov_b32 s22, s12
	s_waitcnt lgkmcnt(1)
	v_mfma_f32_32x32x16_bf16 v[48:63], v[0:3], v[108:111], v[48:63]
	s_mov_b32 s23, s12
	s_mov_b32 s24, s12
	s_mov_b32 s25, s12
	s_mov_b32 s26, s12
	s_mov_b32 s27, s12
	v_mov_b32_e32 v98, v164
	s_add_u32 s100, s90, s4
	s_addc_u32 s101, s91, s5
	s_add_u32 s100, s100, 0x1bc00180
	s_addc_u32 s101, s101, 0
	s_add_i32 s9, s8, -3
	s_waitcnt lgkmcnt(0)
	v_mfma_f32_32x32x16_bf16 v[48:63], v[4:7], v[112:115], v[48:63]
	ds_read_b128 v[0:3], v184 offset:128
	ds_read_b128 v[4:7], v184 offset:160
	ds_read_b128 v[20:23], v184 offset:6784
	ds_read_b128 v[64:67], v184 offset:6816
	v_mov_b32_e32 v191, 0xf149f2ca
	v_mov_b32_e32 v192, 0
	ds_read_b128 v[16:19], v184 offset:6752
	s_waitcnt lgkmcnt(4)
	v_mfma_f32_32x32x16_bf16 v[48:63], v[0:3], v[116:119], v[48:63]
	ds_read_b128 v[0:3], v184 offset:6656
	s_waitcnt lgkmcnt(4)
	v_mfma_f32_32x32x16_bf16 v[48:63], v[4:7], v[120:123], v[48:63]
	ds_read_b128 v[4:7], v184 offset:6688
	s_waitcnt lgkmcnt(1)
	v_mfma_f32_32x32x16_bf16 v[32:47], v[0:3], v[100:103], 0
	ds_read_b128 v[0:3], v184 offset:6720
	s_waitcnt lgkmcnt(1)
	v_mfma_f32_32x32x16_bf16 v[32:47], v[4:7], v[104:107], v[32:47]
	s_waitcnt lgkmcnt(0)
	v_mfma_f32_32x32x16_bf16 v[32:47], v[0:3], v[108:111], v[32:47]
	v_mov_b64_e32 v[0:1], s[12:13]
	v_mov_b64_e32 v[14:15], s[26:27]
	v_mov_b64_e32 v[2:3], s[14:15]
	v_mov_b64_e32 v[4:5], s[16:17]
	v_mov_b64_e32 v[6:7], s[18:19]
	v_mov_b64_e32 v[8:9], s[20:21]
	v_mov_b64_e32 v[10:11], s[22:23]
	v_mfma_f32_32x32x16_bf16 v[32:47], v[16:19], v[112:115], v[32:47]
	v_mov_b32_e32 v176, v166
	v_mov_b32_e32 v178, v168
	v_mov_b64_e32 v[12:13], s[24:25]
	s_mul_i32 s98, s7, 0xc0
	s_add_u32 s98, s98, s44
	s_addc_u32 s99, s45, 0
	s_add_u32 s98, s98, s90
	s_addc_u32 s99, s99, s91
	s_add_u32 s98, s98, 0x15990000
	s_addc_u32 s99, s99, 0
	v_mfma_f32_32x32x16_bf16 v[32:47], v[20:23], v[116:119], v[32:47]
	v_mov_b64_e32 v[30:31], v[14:15]
	s_mov_b32 s13, 1
	s_mov_b32 s4, 2
	s_mov_b32 s16, 4
	v_mov_b64_e32 v[28:29], v[12:13]
	v_mov_b64_e32 v[26:27], v[10:11]
	v_mov_b64_e32 v[24:25], v[8:9]
	v_mfma_f32_32x32x16_bf16 v[32:47], v[64:67], v[120:123], v[32:47]
	v_mov_b64_e32 v[22:23], v[6:7]
	v_mov_b64_e32 v[20:21], v[4:5]
	v_mov_b64_e32 v[18:19], v[2:3]
	v_mov_b64_e32 v[16:17], v[0:1]
	ds_write_b128 v252, v[160:163]
	ds_write_b128 v252, v[164:167] offset:16
	ds_write_b128 v252, v[168:171] offset:32
	ds_write_b128 v252, v[172:175] offset:48
	s_nop 7
	s_nop 7
	v_max_f32_e32 v96, v48, v49
	v_max3_f32 v96, v96, v50, v51
	v_max3_f32 v96, v96, v52, v53
	v_max3_f32 v96, v96, v54, v55
	v_max3_f32 v96, v96, v56, v57
	v_max3_f32 v96, v96, v58, v59
	v_max3_f32 v96, v96, v60, v61
	v_max3_f32 v96, v96, v62, v63
	v_max3_f32 v96, v96, v32, v33
	v_max3_f32 v96, v96, v34, v35
	v_max3_f32 v96, v96, v36, v37
	v_max3_f32 v96, v96, v38, v39
	v_max3_f32 v96, v96, v40, v41
	v_max3_f32 v96, v96, v42, v43
	v_max3_f32 v96, v96, v44, v45
	v_max3_f32 v96, v96, v46, v47
	s_nop 1
	ds_bpermute_b32 v193, v186, v96
	s_waitcnt lgkmcnt(0)
	v_max_f32_e32 v96, v96, v193
	v_sub_f32_e32 v160, 0, v96
	v_sub_f32_e32 v161, 0, v96
	v_sub_f32_e32 v162, 0, v96
	v_sub_f32_e32 v163, 0, v96
	v_sub_f32_e32 v164, 0, v96
	v_sub_f32_e32 v165, 0, v96
	v_sub_f32_e32 v166, 0, v96
	v_sub_f32_e32 v167, 0, v96
	v_sub_f32_e32 v168, 0, v96
	v_sub_f32_e32 v169, 0, v96
	v_sub_f32_e32 v170, 0, v96
	v_sub_f32_e32 v171, 0, v96
	v_sub_f32_e32 v172, 0, v96
	v_sub_f32_e32 v173, 0, v96
	v_sub_f32_e32 v174, 0, v96
	v_sub_f32_e32 v175, 0, v96
	v_sub_f32_e32 v48, v48, v96
	v_sub_f32_e32 v49, v49, v96
	v_sub_f32_e32 v50, v50, v96
	v_sub_f32_e32 v51, v51, v96
	v_sub_f32_e32 v52, v52, v96
	v_sub_f32_e32 v53, v53, v96
	v_sub_f32_e32 v54, v54, v96
	v_sub_f32_e32 v55, v55, v96
	v_sub_f32_e32 v56, v56, v96
	v_sub_f32_e32 v57, v57, v96
	v_sub_f32_e32 v58, v58, v96
	v_sub_f32_e32 v59, v59, v96
	v_sub_f32_e32 v60, v60, v96
	v_sub_f32_e32 v61, v61, v96
	v_sub_f32_e32 v62, v62, v96
	v_sub_f32_e32 v63, v63, v96
	v_sub_f32_e32 v32, v32, v96
	v_sub_f32_e32 v33, v33, v96
	v_sub_f32_e32 v34, v34, v96
	v_sub_f32_e32 v35, v35, v96
	v_sub_f32_e32 v36, v36, v96
	v_sub_f32_e32 v37, v37, v96
	v_sub_f32_e32 v38, v38, v96
	v_sub_f32_e32 v39, v39, v96
	v_sub_f32_e32 v40, v40, v96
	v_sub_f32_e32 v41, v41, v96
	v_sub_f32_e32 v42, v42, v96
	v_sub_f32_e32 v43, v43, v96
	v_sub_f32_e32 v44, v44, v96
	v_sub_f32_e32 v45, v45, v96
	v_sub_f32_e32 v46, v46, v96
	v_sub_f32_e32 v47, v47, v96
.LBB0_2710:
	s_add_i32 s18, s16, -2
	s_cmp_lt_u32 s18, s8
	s_mov_b32 s17, s4
	s_cselect_b64 s[14:15], -1, 0
	s_cmp_ge_u32 s18, s8
	s_mul_i32 s19, s4, 0x3400
	v_lshlrev_b32_e32 v198, 1, v138
	s_barrier
	s_cbranch_scc1 .LBB0_2717
	v_add3_u32 v64, s19, v190, v198
	s_waitcnt vmcnt(1)
	ds_write_b128 v64, v[128:131]
	s_and_saveexec_b64 s[4:5], s[10:11]
	v_lshlrev_b32_e32 v64, 1, v180
	v_lshlrev_b32_e32 v65, 1, v142
	v_add3_u32 v64, s19, v64, v65
	ds_write_b128 v64, v[124:127]
	s_or_b64 exec, exec, s[4:5]
	s_mul_i32 s4, s17, 0x2400
	v_add_u32_e32 v64, s4, v183
	s_add_i32 s4, s16, -1
	s_cmp_ge_u32 s4, s8
	s_waitcnt vmcnt(0)
	ds_write_b128 v64, v[132:135] offset:39936
	s_cbranch_scc1 .LBB0_2717
	global_load_dwordx4 v[128:131], v178, s[98:99]
	s_and_saveexec_b64 s[4:5], s[10:11]
	s_cbranch_execz .LBB0_2716
	global_load_dwordx4 v[124:127], v176, s[98:99]
.LBB0_2716:
	s_or_b64 exec, exec, s[4:5]
	global_load_dwordx4 v[132:135], v98, s[100:101]
	s_add_u32 s98, s98, 0x30000
	s_addc_u32 s99, s99, 0
	s_add_u32 s100, s100, 0x80
	s_addc_u32 s101, s101, 0

.LBB0_2719:
	v_exp_f32_e32 v193, v48
	v_exp_f32_e32 v195, v49
	s_waitcnt lgkmcnt(5)
	v_mfma_f32_32x32x16_bf16 v[80:95], v[228:231], v[116:119], v[80:95]
	ds_read_b128 v[228:231], v227 offset:6784
	v_exp_f32_e32 v196, v50
	v_exp_f32_e32 v197, v51
	s_waitcnt lgkmcnt(5)
	v_mfma_f32_32x32x16_bf16 v[80:95], v[232:235], v[120:123], v[80:95]
	ds_read_b128 v[232:235], v227 offset:6816
	v_exp_f32_e32 v199, v52
	v_exp_f32_e32 v200, v53
	s_waitcnt lgkmcnt(5)
	v_mfma_f32_32x32x16_bf16 v[64:79], v[236:239], v[100:103], v[160:175]
	v_exp_f32_e32 v201, v54
	v_exp_f32_e32 v202, v55
	s_waitcnt lgkmcnt(4)
	v_mfma_f32_32x32x16_bf16 v[64:79], v[240:243], v[104:107], v[64:79]
	v_exp_f32_e32 v203, v56
	v_exp_f32_e32 v204, v57
	s_waitcnt lgkmcnt(3)
	v_mfma_f32_32x32x16_bf16 v[64:79], v[244:247], v[108:111], v[64:79]
	v_exp_f32_e32 v205, v58
	s_waitcnt lgkmcnt(2)
	v_mfma_f32_32x32x16_bf16 v[64:79], v[248:251], v[112:115], v[64:79]
	s_mul_i32 s20, s12, 0x2400
	v_exp_f32_e32 v206, v59
	v_exp_f32_e32 v211, v32
	v_mov_b32_e32 v32, v33
	s_waitcnt lgkmcnt(1)
	v_mfma_f32_32x32x16_bf16 v[64:79], v[228:231], v[116:119], v[64:79]
	v_lshlrev_b32_e32 v33, 1, v185
	v_lshlrev_b32_e32 v96, 1, v253
	v_exp_f32_e32 v207, v60
	s_waitcnt lgkmcnt(0)
	v_mfma_f32_32x32x16_bf16 v[64:79], v[232:235], v[120:123], v[64:79]
	v_add3_u32 v52, s20, v33, v96
	v_exp_f32_e32 v208, v61
	v_add_u32_e32 v58, 0xa800, v52
	v_exp_f32_e32 v209, v62
	v_add_u32_e32 v56, 0x9800, v52
	ds_read_b64 v[52:53], v58 offset:1536
	ds_read_b64 v[54:55], v58 offset:1552
	v_exp_f32_e32 v210, v63
	ds_read_b64 v[48:49], v56 offset:1024
	ds_read_b64 v[50:51], v56 offset:1040
	v_exp_f32_e32 v212, v32
	v_exp_f32_e32 v215, v36
	v_exp_f32_e32 v213, v34
	v_mov_b32_e32 v57, v35
	v_cvt_pk_bf16_f32 v32, v193, v195
	v_cvt_pk_bf16_f32 v33, v196, v197
	v_cvt_pk_bf16_f32 v34, v199, v200
	v_cvt_pk_bf16_f32 v35, v201, v202
	v_exp_f32_e32 v216, v37
	s_waitcnt lgkmcnt(2)
	v_mfma_f32_32x32x16_bf16 v[0:15], v[52:55], v[32:35], v[0:15]
	v_exp_f32_e32 v217, v38
	v_mov_b32_e32 v52, v39
	ds_read_b64 v[36:37], v58 offset:1568
	ds_read_b64 v[38:39], v58 offset:1584
	v_exp_f32_e32 v214, v57
	v_exp_f32_e32 v218, v52
	v_exp_f32_e32 v219, v40
	s_waitcnt lgkmcnt(2)
	v_mfma_f32_32x32x16_bf16 v[16:31], v[48:51], v[32:35], v[16:31]
	ds_read_b64 v[48:49], v56 offset:1056
	ds_read_b64 v[50:51], v56 offset:1072
	v_cvt_pk_bf16_f32 v32, v203, v204
	v_cvt_pk_bf16_f32 v33, v205, v206
	v_cvt_pk_bf16_f32 v34, v207, v208
	v_cvt_pk_bf16_f32 v35, v209, v210
	v_exp_f32_e32 v220, v41
	s_waitcnt lgkmcnt(2)
	v_mfma_f32_32x32x16_bf16 v[0:15], v[36:39], v[32:35], v[0:15]
	ds_read_b64 v[36:37], v58 offset:1600
	ds_read_b64 v[38:39], v58 offset:1616
	v_exp_f32_e32 v221, v42
	v_exp_f32_e32 v222, v43
	v_exp_f32_e32 v223, v44
	s_waitcnt lgkmcnt(2)
	v_mfma_f32_32x32x16_bf16 v[16:31], v[48:51], v[32:35], v[16:31]
	ds_read_b64 v[48:49], v56 offset:1088
	ds_read_b64 v[50:51], v56 offset:1104
	v_cvt_pk_bf16_f32 v32, v211, v212
	v_cvt_pk_bf16_f32 v33, v213, v214
	v_cvt_pk_bf16_f32 v34, v215, v216
	v_cvt_pk_bf16_f32 v35, v217, v218
	v_exp_f32_e32 v224, v45
	ds_read_b64 v[40:41], v56 offset:1120
	ds_read_b64 v[42:43], v56 offset:1136
	s_waitcnt lgkmcnt(4)
	v_mfma_f32_32x32x16_bf16 v[0:15], v[36:39], v[32:35], v[0:15]
	ds_read_b64 v[36:37], v58 offset:1632
	ds_read_b64 v[38:39], v58 offset:1648
	v_exp_f32_e32 v225, v46
	s_add_i32 s4, s16, -4
	s_cmp_ge_u32 s4, s9
	s_waitcnt lgkmcnt(0)
	s_barrier
	v_mfma_f32_32x32x16_bf16 v[16:31], v[48:51], v[32:35], v[16:31]
	v_exp_f32_e32 v226, v47
	v_cvt_pk_bf16_f32 v32, v219, v220
	v_cvt_pk_bf16_f32 v33, v221, v222
	v_cvt_pk_bf16_f32 v34, v223, v224
	v_cvt_pk_bf16_f32 v35, v225, v226
	s_nop 1
	v_mfma_f32_32x32x16_bf16 v[16:31], v[40:43], v[32:35], v[16:31]
	v_mfma_f32_32x32x16_bf16 v[0:15], v[36:39], v[32:35], v[0:15]
	s_cbranch_scc1 .LBB0_2726
	s_mul_i32 s21, s12, 0x3400
	v_add3_u32 v32, s21, v190, v198
	s_waitcnt vmcnt(1)
	ds_write_b128 v32, v[128:131]
	s_and_saveexec_b64 s[4:5], s[10:11]
	v_lshlrev_b32_e32 v32, 1, v180
	v_lshlrev_b32_e32 v33, 1, v142
	v_add3_u32 v32, s21, v32, v33
	ds_write_b128 v32, v[124:127]
	s_or_b64 exec, exec, s[4:5]
	v_lshlrev_b32_e32 v32, 1, v182
	v_add3_u32 v32, s20, v32, v158
	s_cmp_ge_u32 s16, s8
	s_waitcnt vmcnt(0)
	ds_write_b128 v32, v[132:135] offset:39936
	s_cbranch_scc1 .LBB0_2726
	global_load_dwordx4 v[128:131], v178, s[98:99]
	s_and_saveexec_b64 s[4:5], s[10:11]
	s_cbranch_execz .LBB0_2725
	global_load_dwordx4 v[124:127], v176, s[98:99]

.LBB0_2730:
	v_exp_f32_e32 v80, v80
	v_exp_f32_e32 v81, v81
	v_exp_f32_e32 v82, v82
	v_exp_f32_e32 v83, v83
	v_exp_f32_e32 v201, v84
	v_exp_f32_e32 v202, v85
	v_mov_b32_e32 v84, v86
	v_mov_b32_e32 v86, v88
	v_mov_b32_e32 v88, v90
	v_mov_b32_e32 v90, v92
	v_mov_b32_e32 v92, v94
	v_exp_f32_e32 v94, v64
	v_add_f32_e32 v193, 0, v80
	v_exp_f32_e32 v203, v84
	v_mov_b32_e32 v84, v87
	v_mov_b32_e32 v87, v89
	v_mov_b32_e32 v89, v91
	v_mov_b32_e32 v91, v93
	v_mov_b32_e32 v93, v95
	v_exp_f32_e32 v95, v65
	s_mul_i32 s4, s13, 0x2400
	v_add_f32_e32 v195, 0, v81
	v_add_f32_e32 v193, v82, v193
	v_exp_f32_e32 v196, v66
	v_add_f32_e32 v195, v83, v195
	v_exp_f32_e32 v204, v84
	v_add_f32_e32 v84, v201, v193
	v_exp_f32_e32 v197, v67
	v_add_u32_e32 v193, s4, v159
	v_add_f32_e32 v85, v202, v195
	v_exp_f32_e32 v198, v68
	v_add_u32_e32 v195, 0x9800, v193
	v_exp_f32_e32 v199, v69
	ds_read_b64 v[64:65], v195 offset:1024
	ds_read_b64 v[66:67], v195 offset:1040
	v_add_u32_e32 v193, 0xa800, v193
	v_exp_f32_e32 v200, v70
	v_mov_b32_e32 v205, v71
	v_cvt_pk_bf16_f32 v68, v80, v81
	v_cvt_pk_bf16_f32 v69, v82, v83
	v_cvt_pk_bf16_f32 v70, v201, v202
	v_cvt_pk_bf16_f32 v71, v203, v204
	ds_read_b64 v[80:81], v193 offset:1536
	ds_read_b64 v[82:83], v193 offset:1552
	v_add_f32_e32 v84, v203, v84
	s_waitcnt lgkmcnt(2)
	v_mfma_f32_32x32x16_bf16 v[16:31], v[64:67], v[68:71], v[16:31]
	v_exp_f32_e32 v202, v72
	v_exp_f32_e32 v203, v73
	ds_read_b64 v[64:65], v195 offset:1056
	ds_read_b64 v[66:67], v195 offset:1072
	v_exp_f32_e32 v86, v86
	v_exp_f32_e32 v87, v87
	v_exp_f32_e32 v88, v88
	v_exp_f32_e32 v89, v89
	v_exp_f32_e32 v90, v90
	v_exp_f32_e32 v91, v91
	v_exp_f32_e32 v92, v92
	v_exp_f32_e32 v93, v93
	s_waitcnt lgkmcnt(2)
	v_mfma_f32_32x32x16_bf16 v[0:15], v[80:83], v[68:71], v[0:15]
	v_exp_f32_e32 v80, v74
	v_mov_b32_e32 v81, v75
	ds_read_b64 v[72:73], v193 offset:1568
	ds_read_b64 v[74:75], v193 offset:1584
	v_cvt_pk_bf16_f32 v68, v86, v87
	v_cvt_pk_bf16_f32 v69, v88, v89
	v_cvt_pk_bf16_f32 v70, v90, v91
	v_cvt_pk_bf16_f32 v71, v92, v93
	v_exp_f32_e32 v201, v205
	v_add_f32_e32 v85, v204, v85
	s_waitcnt lgkmcnt(2)
	v_mfma_f32_32x32x16_bf16 v[16:31], v[64:67], v[68:71], v[16:31]
	v_exp_f32_e32 v76, v76
	v_exp_f32_e32 v77, v77
	ds_read_b64 v[64:65], v195 offset:1088
	ds_read_b64 v[66:67], v195 offset:1104
	s_waitcnt lgkmcnt(2)
	v_mfma_f32_32x32x16_bf16 v[0:15], v[72:75], v[68:71], v[0:15]
	ds_read_b64 v[72:73], v193 offset:1600
	ds_read_b64 v[74:75], v193 offset:1616
	v_cvt_pk_bf16_f32 v68, v94, v95
	v_cvt_pk_bf16_f32 v69, v196, v197
	v_cvt_pk_bf16_f32 v70, v198, v199
	v_cvt_pk_bf16_f32 v71, v200, v201
	v_exp_f32_e32 v81, v81
	v_exp_f32_e32 v78, v78
	s_waitcnt lgkmcnt(2)
	v_mfma_f32_32x32x16_bf16 v[16:31], v[64:67], v[68:71], v[16:31]
	v_add_f32_e64 v64, v86, v84
	v_add_f32_e64 v65, v87, v85
	v_exp_f32_e32 v79, v79
	v_pk_add_f32 v[64:65], v[88:89], v[64:65]
	s_add_i32 s16, s16, 2
	v_pk_add_f32 v[64:65], v[90:91], v[64:65]
	v_pk_add_f32 v[64:65], v[92:93], v[64:65]
	s_waitcnt lgkmcnt(0)
	v_mfma_f32_32x32x16_bf16 v[0:15], v[72:75], v[68:71], v[0:15]
	v_add_f32_e64 v82, v94, v64
	v_add_f32_e64 v83, v95, v65
	ds_read_b64 v[64:65], v195 offset:1120
	ds_read_b64 v[66:67], v195 offset:1136
	ds_read_b64 v[72:73], v193 offset:1632
	ds_read_b64 v[74:75], v193 offset:1648
	v_add_f32_e64 v68, v196, v82
	v_add_f32_e64 v69, v197, v83
	v_cvt_pk_bf16_f32 v70, v76, v77
	v_pk_add_f32 v[82:83], v[198:199], v[68:69]
	v_cvt_pk_bf16_f32 v68, v202, v203
	v_cvt_pk_bf16_f32 v69, v80, v81
	v_cvt_pk_bf16_f32 v71, v78, v79
	s_cmp_ge_u32 s18, s8
	s_waitcnt lgkmcnt(2)
	v_mfma_f32_32x32x16_bf16 v[16:31], v[64:67], v[68:71], v[16:31]
	v_add_f32_e64 v64, v200, v82
	v_add_f32_e64 v65, v201, v83
	v_add_f32_e64 v64, v202, v64
	v_add_f32_e64 v65, v203, v65
	v_pk_add_f32 v[64:65], v[80:81], v[64:65]
	s_nop 0
	v_pk_add_f32 v[64:65], v[76:77], v[64:65]
	s_waitcnt lgkmcnt(0)
	v_mfma_f32_32x32x16_bf16 v[0:15], v[72:75], v[68:71], v[0:15]
	v_add_f32_e64 v64, v78, v64
	v_add_f32_e64 v65, v79, v65
	v_add_f32_e32 v64, v64, v65
	v_add_f32_e32 v192, v192, v64
	s_cbranch_scc1 .LBB0_2693
	s_mov_b32 s4, s13
	s_mov_b32 s13, s12
	s_mov_b32 s12, s17
	s_branch .LBB0_2710
